# v19 + streamlined epilogues for the paired (PAIRMUL/SWIGLU) and SIGMOID tiles: every epilogue kind now runs without per-16-row dispatch
# speedup vs baseline: 1.0076x; 1.0076x over previous
;     __device__ __forceinline__ void operator()(const f32x4 (&acc)[2][2][4][2], const Unit& u, int wr, int wc, int fr, int fq) const {
;         int k = kind; size_t ob = oO; int ld = ldc; int colt = u.pn * BM; const float sc = scale;
;         if (k == EK_WIN) {
;             const int pn = u.pn;
;             if (pn < 4) { k = EK_PLAIN; }
;             else if (pn < 12) { k = EK_PAIRMUL; ob = WS_U; colt = (pn - 4) * 128; }
;             else if (pn < 16) { k = EK_SIGMOID; ob = WS_R1; colt = (pn - 12) * 256; }
;             else if (pn < 20) { k = EK_SIGMOID; ob = WS_R2; colt = (pn - 16) * 256; }
;             else { k = EK_PLAIN; ob = WS_LAT; colt = (pn - 20) * 256; ld = 768; }
;         } else if (k == EK_Q) {
;             k = EK_PLAIN; if (u.pn >= 4) { ob = WS_QR; colt = (u.pn - 4) * 256; ld = 512; }
;         } else if (k == EK_PAIRMUL || k == EK_SWIGLU) colt = u.pn * 128;
;         const int row0 = u.pm * BM + wr * 64 + fr;
;         const int col0 = colt + wc * 32 + 8 * fq;
;         bf16_t* base = (bf16_t*)(ws + ob); const bf16_t* aux1 = (const bf16_t*)(ws + WS_R1); const bf16_t* aux2 = (const bf16_t*)(ws + WS_R2);
;         const float* rsp = (const float*)(ws + oRS);
;         if (k == EK_PAIRMUL || k == EK_SWIGLU) {
.Lepi_rs_done:
	s_cmp_eq_u32 s36, 3
	s_cbranch_scc1 .Lepi_sig_fast
	s_cmp_eq_u32 s36, 2
	s_cbranch_scc1 .Lepi_swiglu_fast
	s_cmp_eq_u32 s36, 1
	s_cbranch_scc1 .Lepi_pair_fast
	s_cmp_eq_u32 s36, 4
	s_cbranch_scc1 .Lepi_gate_fast
	s_cmp_eq_u32 s36, 5
	s_cbranch_scc1 .Lepi_comb_fast
	s_cmp_eq_u32 s36, 0
	s_cbranch_scc1 .Lepi_plain_fast
	s_and_b64 vcc, exec, s[30:31]
	s_cbranch_vccnz .LBB0_717
	s_cmp_lt_i32 s75, 15
	s_cbranch_scc1 .LBB0_720
	s_cmp_eq_u32 s75, 15
	s_cselect_b64 s[8:9], -1, 0
	s_cbranch_execz .LBB0_721
	s_branch .LBB0_722

; __device__ __forceinline__ unsigned cvt_pk_bf16(float lo, float hi) { unsigned r; asm volatile("v_cvt_pk_bf16_f32 %0, %1, %2" : "=v"(r) : "v"(lo), "v"(hi)); return r; }
; __device__ __forceinline__ float sigm(float x) { return __builtin_amdgcn_rcpf(1.0f + __builtin_amdgcn_exp2f(-1.4426950408889634f * x)); }
;     __device__ __forceinline__ void operator()(const f32x4 (&acc)[2][2][4][2], const Unit& u, int wr, int wc, int fr, int fq) const {
;     ...
;         if (k == EK_PAIRMUL || k == EK_SWIGLU) {
; #pragma unroll
;             for (int ai = 0; ai < 2; ++ai)
; #pragma unroll
;                 for (int m = 0; m < 4; ++m) {
;                     bf16_t* rowp = base + (size_t)(row0 + ai * HALF + m * 16) * ld + col0;
;                     const float rr = use_rs ? rsp[row0 + ai * HALF + m * 16] : 1.f;
;                     f32x4 a0 = acc[ai][0][m][0] * rr, a1 = acc[ai][0][m][1] * rr; const f32x4 b0 = acc[ai][1][m][0] * rr, b1 = acc[ai][1][m][1] * rr;
;                     if (k == EK_SWIGLU) {
; #pragma unroll
;                         for (int i = 0; i < 4; ++i) { a0[i] = a0[i] * sigm(a0[i]); a1[i] = a1[i] * sigm(a1[i]); }
;                     }
;                     const f32x4 v0 = a0 * b0, v1 = a1 * b1;
;                     u32x4e w; w.x = cvt_pk_bf16(v0[0], v0[1]); w.y = cvt_pk_bf16(v0[2], v0[3]); w.z = cvt_pk_bf16(v1[0], v1[1]); w.w = cvt_pk_bf16(v1[2], v1[3]);
;                     *(u32x4e*)rowp = w;
;                 }
.Lepi_pair_fast:
	v_mad_i64_i32 v[148:149], s[8:9], s27, v140, v[142:143]
	s_lshl_b32 s16, s27, 5
	s_mov_b32 s17, 0
	s_mul_i32 s30, s27, 0xa0
	s_mov_b32 s31, 0
	v_lshl_add_u64 v[150:151], v[148:149], 1, s[40:41]
	v_mov_b32_e32 v146, v182
	v_mov_b32_e32 v147, v182
	v_pk_mul_f32 v[126:127], v[126:127], v[146:147]
	v_pk_mul_f32 v[128:129], v[128:129], v[146:147]
	v_pk_mul_f32 v[122:123], v[122:123], v[146:147]
	v_pk_mul_f32 v[124:125], v[124:125], v[146:147]
	v_pk_mul_f32 v[118:119], v[118:119], v[146:147]
	v_pk_mul_f32 v[120:121], v[120:121], v[146:147]
	v_pk_mul_f32 v[114:115], v[114:115], v[146:147]
	v_pk_mul_f32 v[116:117], v[116:117], v[146:147]
	v_pk_mul_f32 v[118:119], v[118:119], v[126:127]
	v_pk_mul_f32 v[120:121], v[120:121], v[128:129]
	v_pk_mul_f32 v[114:115], v[114:115], v[122:123]
	v_pk_mul_f32 v[116:117], v[116:117], v[124:125]
	v_cvt_pk_bf16_f32 v172, v118, v119
	v_cvt_pk_bf16_f32 v173, v120, v121
	v_cvt_pk_bf16_f32 v174, v114, v115
	v_cvt_pk_bf16_f32 v175, v116, v117
	global_store_dwordx4 v[150:151], v[172:175], off
	v_lshl_add_u64 v[150:151], v[150:151], 0, s[16:17]
	v_mov_b32_e32 v146, v183
	v_mov_b32_e32 v147, v183
	v_pk_mul_f32 v[110:111], v[110:111], v[146:147]
	v_pk_mul_f32 v[112:113], v[112:113], v[146:147]
	v_pk_mul_f32 v[106:107], v[106:107], v[146:147]
	v_pk_mul_f32 v[108:109], v[108:109], v[146:147]
	v_pk_mul_f32 v[102:103], v[102:103], v[146:147]
	v_pk_mul_f32 v[104:105], v[104:105], v[146:147]
	v_pk_mul_f32 v[98:99], v[98:99], v[146:147]
	v_pk_mul_f32 v[100:101], v[100:101], v[146:147]
	v_pk_mul_f32 v[102:103], v[102:103], v[110:111]
	v_pk_mul_f32 v[104:105], v[104:105], v[112:113]
	v_pk_mul_f32 v[98:99], v[98:99], v[106:107]
	v_pk_mul_f32 v[100:101], v[100:101], v[108:109]
	v_cvt_pk_bf16_f32 v176, v102, v103
	v_cvt_pk_bf16_f32 v177, v104, v105
	v_cvt_pk_bf16_f32 v178, v98, v99
	v_cvt_pk_bf16_f32 v179, v100, v101
	global_store_dwordx4 v[150:151], v[176:179], off
	v_lshl_add_u64 v[150:151], v[150:151], 0, s[16:17]
	v_mov_b32_e32 v146, v184
	v_mov_b32_e32 v147, v184
	v_pk_mul_f32 v[94:95], v[94:95], v[146:147]
	v_pk_mul_f32 v[96:97], v[96:97], v[146:147]
	v_pk_mul_f32 v[90:91], v[90:91], v[146:147]
	v_pk_mul_f32 v[92:93], v[92:93], v[146:147]
	v_pk_mul_f32 v[86:87], v[86:87], v[146:147]
	v_pk_mul_f32 v[88:89], v[88:89], v[146:147]
	v_pk_mul_f32 v[82:83], v[82:83], v[146:147]
	v_pk_mul_f32 v[84:85], v[84:85], v[146:147]
	v_pk_mul_f32 v[86:87], v[86:87], v[94:95]
	v_pk_mul_f32 v[88:89], v[88:89], v[96:97]
	v_pk_mul_f32 v[82:83], v[82:83], v[90:91]
	v_pk_mul_f32 v[84:85], v[84:85], v[92:93]
	v_cvt_pk_bf16_f32 v172, v86, v87
	v_cvt_pk_bf16_f32 v173, v88, v89
	v_cvt_pk_bf16_f32 v174, v82, v83
	v_cvt_pk_bf16_f32 v175, v84, v85
	global_store_dwordx4 v[150:151], v[172:175], off
	v_lshl_add_u64 v[150:151], v[150:151], 0, s[16:17]
	v_mov_b32_e32 v146, v185
	v_mov_b32_e32 v147, v185
	v_pk_mul_f32 v[78:79], v[78:79], v[146:147]
	v_pk_mul_f32 v[80:81], v[80:81], v[146:147]
	v_pk_mul_f32 v[74:75], v[74:75], v[146:147]
	v_pk_mul_f32 v[76:77], v[76:77], v[146:147]
	v_pk_mul_f32 v[70:71], v[70:71], v[146:147]
	v_pk_mul_f32 v[72:73], v[72:73], v[146:147]
	v_pk_mul_f32 v[66:67], v[66:67], v[146:147]
	v_pk_mul_f32 v[68:69], v[68:69], v[146:147]
	v_pk_mul_f32 v[70:71], v[70:71], v[78:79]
	v_pk_mul_f32 v[72:73], v[72:73], v[80:81]
	v_pk_mul_f32 v[66:67], v[66:67], v[74:75]
	v_pk_mul_f32 v[68:69], v[68:69], v[76:77]
	v_cvt_pk_bf16_f32 v176, v70, v71
	v_cvt_pk_bf16_f32 v177, v72, v73
	v_cvt_pk_bf16_f32 v178, v66, v67
	v_cvt_pk_bf16_f32 v179, v68, v69
	global_store_dwordx4 v[150:151], v[176:179], off
	v_lshl_add_u64 v[150:151], v[150:151], 0, s[30:31]
	v_mov_b32_e32 v146, v186
	v_mov_b32_e32 v147, v186
	v_pk_mul_f32 v[60:61], v[60:61], v[146:147]
	v_pk_mul_f32 v[62:63], v[62:63], v[146:147]
	v_pk_mul_f32 v[56:57], v[56:57], v[146:147]
	v_pk_mul_f32 v[58:59], v[58:59], v[146:147]
	v_pk_mul_f32 v[52:53], v[52:53], v[146:147]
	v_pk_mul_f32 v[54:55], v[54:55], v[146:147]
	v_pk_mul_f32 v[48:49], v[48:49], v[146:147]
	v_pk_mul_f32 v[50:51], v[50:51], v[146:147]
	v_pk_mul_f32 v[52:53], v[52:53], v[60:61]
	v_pk_mul_f32 v[54:55], v[54:55], v[62:63]
	v_pk_mul_f32 v[48:49], v[48:49], v[56:57]
	v_pk_mul_f32 v[50:51], v[50:51], v[58:59]
	v_cvt_pk_bf16_f32 v172, v52, v53
	v_cvt_pk_bf16_f32 v173, v54, v55
	v_cvt_pk_bf16_f32 v174, v48, v49
	v_cvt_pk_bf16_f32 v175, v50, v51
	global_store_dwordx4 v[150:151], v[172:175], off
	v_lshl_add_u64 v[150:151], v[150:151], 0, s[16:17]
	v_mov_b32_e32 v146, v187
	v_mov_b32_e32 v147, v187
	v_pk_mul_f32 v[44:45], v[44:45], v[146:147]
	v_pk_mul_f32 v[46:47], v[46:47], v[146:147]
	v_pk_mul_f32 v[40:41], v[40:41], v[146:147]
	v_pk_mul_f32 v[42:43], v[42:43], v[146:147]
	v_pk_mul_f32 v[36:37], v[36:37], v[146:147]
	v_pk_mul_f32 v[38:39], v[38:39], v[146:147]
	v_pk_mul_f32 v[32:33], v[32:33], v[146:147]
	v_pk_mul_f32 v[34:35], v[34:35], v[146:147]
	v_pk_mul_f32 v[36:37], v[36:37], v[44:45]
	v_pk_mul_f32 v[38:39], v[38:39], v[46:47]
	v_pk_mul_f32 v[32:33], v[32:33], v[40:41]
	v_pk_mul_f32 v[34:35], v[34:35], v[42:43]
	v_cvt_pk_bf16_f32 v176, v36, v37
	v_cvt_pk_bf16_f32 v177, v38, v39
	v_cvt_pk_bf16_f32 v178, v32, v33
	v_cvt_pk_bf16_f32 v179, v34, v35
	global_store_dwordx4 v[150:151], v[176:179], off
	v_lshl_add_u64 v[150:151], v[150:151], 0, s[16:17]
	v_mov_b32_e32 v146, v188
	v_mov_b32_e32 v147, v188
	v_pk_mul_f32 v[28:29], v[28:29], v[146:147]
	v_pk_mul_f32 v[30:31], v[30:31], v[146:147]
	v_pk_mul_f32 v[24:25], v[24:25], v[146:147]
	v_pk_mul_f32 v[26:27], v[26:27], v[146:147]
	v_pk_mul_f32 v[20:21], v[20:21], v[146:147]
	v_pk_mul_f32 v[22:23], v[22:23], v[146:147]
	v_pk_mul_f32 v[16:17], v[16:17], v[146:147]
	v_pk_mul_f32 v[18:19], v[18:19], v[146:147]
	v_pk_mul_f32 v[20:21], v[20:21], v[28:29]
	v_pk_mul_f32 v[22:23], v[22:23], v[30:31]
	v_pk_mul_f32 v[16:17], v[16:17], v[24:25]
	v_pk_mul_f32 v[18:19], v[18:19], v[26:27]
	v_cvt_pk_bf16_f32 v172, v20, v21
	v_cvt_pk_bf16_f32 v173, v22, v23
	v_cvt_pk_bf16_f32 v174, v16, v17
	v_cvt_pk_bf16_f32 v175, v18, v19
	global_store_dwordx4 v[150:151], v[172:175], off
	v_lshl_add_u64 v[150:151], v[150:151], 0, s[16:17]
	v_mov_b32_e32 v146, v189
	v_mov_b32_e32 v147, v189
	v_pk_mul_f32 v[12:13], v[12:13], v[146:147]
	v_pk_mul_f32 v[14:15], v[14:15], v[146:147]
	v_pk_mul_f32 v[8:9], v[8:9], v[146:147]
	v_pk_mul_f32 v[10:11], v[10:11], v[146:147]
	v_pk_mul_f32 v[4:5], v[4:5], v[146:147]
	v_pk_mul_f32 v[6:7], v[6:7], v[146:147]
	v_pk_mul_f32 v[0:1], v[0:1], v[146:147]
	v_pk_mul_f32 v[2:3], v[2:3], v[146:147]
	v_pk_mul_f32 v[4:5], v[4:5], v[12:13]
	v_pk_mul_f32 v[6:7], v[6:7], v[14:15]
	v_pk_mul_f32 v[0:1], v[0:1], v[8:9]
	v_pk_mul_f32 v[2:3], v[2:3], v[10:11]
	v_cvt_pk_bf16_f32 v176, v4, v5
	v_cvt_pk_bf16_f32 v177, v6, v7
	v_cvt_pk_bf16_f32 v178, v0, v1
	v_cvt_pk_bf16_f32 v179, v2, v3
	global_store_dwordx4 v[150:151], v[176:179], off
	s_branch .LBB0_967
; __device__ __forceinline__ unsigned cvt_pk_bf16(float lo, float hi) { unsigned r; asm volatile("v_cvt_pk_bf16_f32 %0, %1, %2" : "=v"(r) : "v"(lo), "v"(hi)); return r; }
; __device__ __forceinline__ float sigm(float x) { return __builtin_amdgcn_rcpf(1.0f + __builtin_amdgcn_exp2f(-1.4426950408889634f * x)); }
;     __device__ __forceinline__ void operator()(const f32x4 (&acc)[2][2][4][2], const Unit& u, int wr, int wc, int fr, int fq) const {
;     ...
;                     bf16_t* rowp = base + (size_t)(row0 + ai * HALF + m * 16) * ld + col0;
;                     const float rr = use_rs ? rsp[row0 + ai * HALF + m * 16] : 1.f;
;                     f32x4 a0 = acc[ai][0][m][0] * rr, a1 = acc[ai][0][m][1] * rr; const f32x4 b0 = acc[ai][1][m][0] * rr, b1 = acc[ai][1][m][1] * rr;
;                     if (k == EK_SWIGLU) {
; #pragma unroll
;                         for (int i = 0; i < 4; ++i) { a0[i] = a0[i] * sigm(a0[i]); a1[i] = a1[i] * sigm(a1[i]); }
;                     }
;                     const f32x4 v0 = a0 * b0, v1 = a1 * b1;
;                     u32x4e w; w.x = cvt_pk_bf16(v0[0], v0[1]); w.y = cvt_pk_bf16(v0[2], v0[3]); w.z = cvt_pk_bf16(v1[0], v1[1]); w.w = cvt_pk_bf16(v1[2], v1[3]);
;                     *(u32x4e*)rowp = w;
.Lepi_swiglu_fast:
	v_mad_i64_i32 v[148:149], s[8:9], s27, v140, v[142:143]
	s_lshl_b32 s16, s27, 5
	s_mov_b32 s17, 0
	s_mul_i32 s30, s27, 0xa0
	s_mov_b32 s31, 0
	v_lshl_add_u64 v[150:151], v[148:149], 1, s[40:41]
	v_mov_b32_e32 v146, v182
	v_mov_b32_e32 v147, v182
	v_pk_mul_f32 v[126:127], v[126:127], v[146:147]
	v_pk_mul_f32 v[128:129], v[128:129], v[146:147]
	v_pk_mul_f32 v[122:123], v[122:123], v[146:147]
	v_pk_mul_f32 v[124:125], v[124:125], v[146:147]
	v_pk_mul_f32 v[118:119], v[118:119], v[146:147]
	v_pk_mul_f32 v[120:121], v[120:121], v[146:147]
	v_pk_mul_f32 v[114:115], v[114:115], v[146:147]
	v_pk_mul_f32 v[116:117], v[116:117], v[146:147]
	v_mul_f32_e32 v152, 0xbfb8aa3b, v126
	v_mul_f32_e32 v153, 0xbfb8aa3b, v127
	v_mul_f32_e32 v154, 0xbfb8aa3b, v128
	v_mul_f32_e32 v155, 0xbfb8aa3b, v129
	v_mul_f32_e32 v156, 0xbfb8aa3b, v122
	v_mul_f32_e32 v157, 0xbfb8aa3b, v123
	v_mul_f32_e32 v158, 0xbfb8aa3b, v124
	v_mul_f32_e32 v159, 0xbfb8aa3b, v125
	v_exp_f32_e32 v152, v152
	v_exp_f32_e32 v153, v153
	v_exp_f32_e32 v154, v154
	v_exp_f32_e32 v155, v155
	v_exp_f32_e32 v156, v156
	v_exp_f32_e32 v157, v157
	v_exp_f32_e32 v158, v158
	v_exp_f32_e32 v159, v159
	v_add_f32_e32 v152, 1.0, v152
	v_add_f32_e32 v153, 1.0, v153
	v_add_f32_e32 v154, 1.0, v154
	v_add_f32_e32 v155, 1.0, v155
	v_add_f32_e32 v156, 1.0, v156
	v_add_f32_e32 v157, 1.0, v157
	v_add_f32_e32 v158, 1.0, v158
	v_add_f32_e32 v159, 1.0, v159
	v_rcp_f32_e32 v152, v152
	v_rcp_f32_e32 v153, v153
	v_rcp_f32_e32 v154, v154
	v_rcp_f32_e32 v155, v155
	v_rcp_f32_e32 v156, v156
	v_rcp_f32_e32 v157, v157
	v_rcp_f32_e32 v158, v158
	v_rcp_f32_e32 v159, v159
	v_pk_mul_f32 v[126:127], v[126:127], v[152:153]
	v_pk_mul_f32 v[128:129], v[128:129], v[154:155]
	v_pk_mul_f32 v[122:123], v[122:123], v[156:157]
	v_pk_mul_f32 v[124:125], v[124:125], v[158:159]
	v_pk_mul_f32 v[118:119], v[118:119], v[126:127]
	v_pk_mul_f32 v[120:121], v[120:121], v[128:129]
	v_pk_mul_f32 v[114:115], v[114:115], v[122:123]
	v_pk_mul_f32 v[116:117], v[116:117], v[124:125]
	v_cvt_pk_bf16_f32 v172, v118, v119
	v_cvt_pk_bf16_f32 v173, v120, v121
	v_cvt_pk_bf16_f32 v174, v114, v115
	v_cvt_pk_bf16_f32 v175, v116, v117
	global_store_dwordx4 v[150:151], v[172:175], off
	v_lshl_add_u64 v[150:151], v[150:151], 0, s[16:17]
	v_mov_b32_e32 v146, v183
	v_mov_b32_e32 v147, v183
	v_pk_mul_f32 v[110:111], v[110:111], v[146:147]
	v_pk_mul_f32 v[112:113], v[112:113], v[146:147]
	v_pk_mul_f32 v[106:107], v[106:107], v[146:147]
	v_pk_mul_f32 v[108:109], v[108:109], v[146:147]
	v_pk_mul_f32 v[102:103], v[102:103], v[146:147]
	v_pk_mul_f32 v[104:105], v[104:105], v[146:147]
	v_pk_mul_f32 v[98:99], v[98:99], v[146:147]
	v_pk_mul_f32 v[100:101], v[100:101], v[146:147]
	v_mul_f32_e32 v152, 0xbfb8aa3b, v110
	v_mul_f32_e32 v153, 0xbfb8aa3b, v111
	v_mul_f32_e32 v154, 0xbfb8aa3b, v112
	v_mul_f32_e32 v155, 0xbfb8aa3b, v113
	v_mul_f32_e32 v156, 0xbfb8aa3b, v106
	v_mul_f32_e32 v157, 0xbfb8aa3b, v107
	v_mul_f32_e32 v158, 0xbfb8aa3b, v108
	v_mul_f32_e32 v159, 0xbfb8aa3b, v109
	v_exp_f32_e32 v152, v152
	v_exp_f32_e32 v153, v153
	v_exp_f32_e32 v154, v154
	v_exp_f32_e32 v155, v155
	v_exp_f32_e32 v156, v156
	v_exp_f32_e32 v157, v157
	v_exp_f32_e32 v158, v158
	v_exp_f32_e32 v159, v159
	v_add_f32_e32 v152, 1.0, v152
	v_add_f32_e32 v153, 1.0, v153
	v_add_f32_e32 v154, 1.0, v154
	v_add_f32_e32 v155, 1.0, v155
	v_add_f32_e32 v156, 1.0, v156
	v_add_f32_e32 v157, 1.0, v157
	v_add_f32_e32 v158, 1.0, v158
	v_add_f32_e32 v159, 1.0, v159
	v_rcp_f32_e32 v152, v152
	v_rcp_f32_e32 v153, v153
	v_rcp_f32_e32 v154, v154
	v_rcp_f32_e32 v155, v155
	v_rcp_f32_e32 v156, v156
	v_rcp_f32_e32 v157, v157
	v_rcp_f32_e32 v158, v158
	v_rcp_f32_e32 v159, v159
	v_pk_mul_f32 v[110:111], v[110:111], v[152:153]
	v_pk_mul_f32 v[112:113], v[112:113], v[154:155]
	v_pk_mul_f32 v[106:107], v[106:107], v[156:157]
	v_pk_mul_f32 v[108:109], v[108:109], v[158:159]
	v_pk_mul_f32 v[102:103], v[102:103], v[110:111]
	v_pk_mul_f32 v[104:105], v[104:105], v[112:113]
	v_pk_mul_f32 v[98:99], v[98:99], v[106:107]
	v_pk_mul_f32 v[100:101], v[100:101], v[108:109]
	v_cvt_pk_bf16_f32 v176, v102, v103
	v_cvt_pk_bf16_f32 v177, v104, v105
	v_cvt_pk_bf16_f32 v178, v98, v99
	v_cvt_pk_bf16_f32 v179, v100, v101
	global_store_dwordx4 v[150:151], v[176:179], off
	v_lshl_add_u64 v[150:151], v[150:151], 0, s[16:17]
	v_mov_b32_e32 v146, v184
	v_mov_b32_e32 v147, v184
	v_pk_mul_f32 v[94:95], v[94:95], v[146:147]
	v_pk_mul_f32 v[96:97], v[96:97], v[146:147]
	v_pk_mul_f32 v[90:91], v[90:91], v[146:147]
	v_pk_mul_f32 v[92:93], v[92:93], v[146:147]
	v_pk_mul_f32 v[86:87], v[86:87], v[146:147]
	v_pk_mul_f32 v[88:89], v[88:89], v[146:147]
	v_pk_mul_f32 v[82:83], v[82:83], v[146:147]
	v_pk_mul_f32 v[84:85], v[84:85], v[146:147]
	v_mul_f32_e32 v152, 0xbfb8aa3b, v94
	v_mul_f32_e32 v153, 0xbfb8aa3b, v95
	v_mul_f32_e32 v154, 0xbfb8aa3b, v96
	v_mul_f32_e32 v155, 0xbfb8aa3b, v97
	v_mul_f32_e32 v156, 0xbfb8aa3b, v90
	v_mul_f32_e32 v157, 0xbfb8aa3b, v91
	v_mul_f32_e32 v158, 0xbfb8aa3b, v92
	v_mul_f32_e32 v159, 0xbfb8aa3b, v93
	v_exp_f32_e32 v152, v152
	v_exp_f32_e32 v153, v153
	v_exp_f32_e32 v154, v154
	v_exp_f32_e32 v155, v155
	v_exp_f32_e32 v156, v156
	v_exp_f32_e32 v157, v157
	v_exp_f32_e32 v158, v158
	v_exp_f32_e32 v159, v159
	v_add_f32_e32 v152, 1.0, v152
	v_add_f32_e32 v153, 1.0, v153
	v_add_f32_e32 v154, 1.0, v154
	v_add_f32_e32 v155, 1.0, v155
	v_add_f32_e32 v156, 1.0, v156
	v_add_f32_e32 v157, 1.0, v157
	v_add_f32_e32 v158, 1.0, v158
	v_add_f32_e32 v159, 1.0, v159
	v_rcp_f32_e32 v152, v152
	v_rcp_f32_e32 v153, v153
	v_rcp_f32_e32 v154, v154
	v_rcp_f32_e32 v155, v155
	v_rcp_f32_e32 v156, v156
	v_rcp_f32_e32 v157, v157
	v_rcp_f32_e32 v158, v158
; __device__ __forceinline__ unsigned cvt_pk_bf16(float lo, float hi) { unsigned r; asm volatile("v_cvt_pk_bf16_f32 %0, %1, %2" : "=v"(r) : "v"(lo), "v"(hi)); return r; }
; __device__ __forceinline__ float sigm(float x) { return __builtin_amdgcn_rcpf(1.0f + __builtin_amdgcn_exp2f(-1.4426950408889634f * x)); }
;     __device__ __forceinline__ void operator()(const f32x4 (&acc)[2][2][4][2], const Unit& u, int wr, int wc, int fr, int fq) const {
;     ...
;                     bf16_t* rowp = base + (size_t)(row0 + ai * HALF + m * 16) * ld + col0;
;                     const float rr = use_rs ? rsp[row0 + ai * HALF + m * 16] : 1.f;
;                     f32x4 a0 = acc[ai][0][m][0] * rr, a1 = acc[ai][0][m][1] * rr; const f32x4 b0 = acc[ai][1][m][0] * rr, b1 = acc[ai][1][m][1] * rr;
;                     if (k == EK_SWIGLU) {
; #pragma unroll
;                         for (int i = 0; i < 4; ++i) { a0[i] = a0[i] * sigm(a0[i]); a1[i] = a1[i] * sigm(a1[i]); }
;                     }
;                     const f32x4 v0 = a0 * b0, v1 = a1 * b1;
;                     u32x4e w; w.x = cvt_pk_bf16(v0[0], v0[1]); w.y = cvt_pk_bf16(v0[2], v0[3]); w.z = cvt_pk_bf16(v1[0], v1[1]); w.w = cvt_pk_bf16(v1[2], v1[3]);
;                     *(u32x4e*)rowp = w;
	v_rcp_f32_e32 v159, v159
	v_pk_mul_f32 v[94:95], v[94:95], v[152:153]
	v_pk_mul_f32 v[96:97], v[96:97], v[154:155]
	v_pk_mul_f32 v[90:91], v[90:91], v[156:157]
	v_pk_mul_f32 v[92:93], v[92:93], v[158:159]
	v_pk_mul_f32 v[86:87], v[86:87], v[94:95]
	v_pk_mul_f32 v[88:89], v[88:89], v[96:97]
	v_pk_mul_f32 v[82:83], v[82:83], v[90:91]
	v_pk_mul_f32 v[84:85], v[84:85], v[92:93]
	v_cvt_pk_bf16_f32 v172, v86, v87
	v_cvt_pk_bf16_f32 v173, v88, v89
	v_cvt_pk_bf16_f32 v174, v82, v83
	v_cvt_pk_bf16_f32 v175, v84, v85
	global_store_dwordx4 v[150:151], v[172:175], off
	v_lshl_add_u64 v[150:151], v[150:151], 0, s[16:17]
	v_mov_b32_e32 v146, v185
	v_mov_b32_e32 v147, v185
	v_pk_mul_f32 v[78:79], v[78:79], v[146:147]
	v_pk_mul_f32 v[80:81], v[80:81], v[146:147]
	v_pk_mul_f32 v[74:75], v[74:75], v[146:147]
	v_pk_mul_f32 v[76:77], v[76:77], v[146:147]
	v_pk_mul_f32 v[70:71], v[70:71], v[146:147]
	v_pk_mul_f32 v[72:73], v[72:73], v[146:147]
	v_pk_mul_f32 v[66:67], v[66:67], v[146:147]
	v_pk_mul_f32 v[68:69], v[68:69], v[146:147]
	v_mul_f32_e32 v152, 0xbfb8aa3b, v78
	v_mul_f32_e32 v153, 0xbfb8aa3b, v79
	v_mul_f32_e32 v154, 0xbfb8aa3b, v80
	v_mul_f32_e32 v155, 0xbfb8aa3b, v81
	v_mul_f32_e32 v156, 0xbfb8aa3b, v74
	v_mul_f32_e32 v157, 0xbfb8aa3b, v75
	v_mul_f32_e32 v158, 0xbfb8aa3b, v76
	v_mul_f32_e32 v159, 0xbfb8aa3b, v77
	v_exp_f32_e32 v152, v152
	v_exp_f32_e32 v153, v153
	v_exp_f32_e32 v154, v154
	v_exp_f32_e32 v155, v155
	v_exp_f32_e32 v156, v156
	v_exp_f32_e32 v157, v157
	v_exp_f32_e32 v158, v158
	v_exp_f32_e32 v159, v159
	v_add_f32_e32 v152, 1.0, v152
	v_add_f32_e32 v153, 1.0, v153
	v_add_f32_e32 v154, 1.0, v154
	v_add_f32_e32 v155, 1.0, v155
	v_add_f32_e32 v156, 1.0, v156
	v_add_f32_e32 v157, 1.0, v157
	v_add_f32_e32 v158, 1.0, v158
	v_add_f32_e32 v159, 1.0, v159
	v_rcp_f32_e32 v152, v152
	v_rcp_f32_e32 v153, v153
	v_rcp_f32_e32 v154, v154
	v_rcp_f32_e32 v155, v155
	v_rcp_f32_e32 v156, v156
	v_rcp_f32_e32 v157, v157
	v_rcp_f32_e32 v158, v158
	v_rcp_f32_e32 v159, v159
	v_pk_mul_f32 v[78:79], v[78:79], v[152:153]
	v_pk_mul_f32 v[80:81], v[80:81], v[154:155]
	v_pk_mul_f32 v[74:75], v[74:75], v[156:157]
	v_pk_mul_f32 v[76:77], v[76:77], v[158:159]
	v_pk_mul_f32 v[70:71], v[70:71], v[78:79]
	v_pk_mul_f32 v[72:73], v[72:73], v[80:81]
	v_pk_mul_f32 v[66:67], v[66:67], v[74:75]
	v_pk_mul_f32 v[68:69], v[68:69], v[76:77]
	v_cvt_pk_bf16_f32 v176, v70, v71
	v_cvt_pk_bf16_f32 v177, v72, v73
	v_cvt_pk_bf16_f32 v178, v66, v67
	v_cvt_pk_bf16_f32 v179, v68, v69
	global_store_dwordx4 v[150:151], v[176:179], off
	v_lshl_add_u64 v[150:151], v[150:151], 0, s[30:31]
	v_mov_b32_e32 v146, v186
	v_mov_b32_e32 v147, v186
	v_pk_mul_f32 v[60:61], v[60:61], v[146:147]
	v_pk_mul_f32 v[62:63], v[62:63], v[146:147]
	v_pk_mul_f32 v[56:57], v[56:57], v[146:147]
	v_pk_mul_f32 v[58:59], v[58:59], v[146:147]
	v_pk_mul_f32 v[52:53], v[52:53], v[146:147]
	v_pk_mul_f32 v[54:55], v[54:55], v[146:147]
	v_pk_mul_f32 v[48:49], v[48:49], v[146:147]
	v_pk_mul_f32 v[50:51], v[50:51], v[146:147]
	v_mul_f32_e32 v152, 0xbfb8aa3b, v60
	v_mul_f32_e32 v153, 0xbfb8aa3b, v61
	v_mul_f32_e32 v154, 0xbfb8aa3b, v62
	v_mul_f32_e32 v155, 0xbfb8aa3b, v63
	v_mul_f32_e32 v156, 0xbfb8aa3b, v56
	v_mul_f32_e32 v157, 0xbfb8aa3b, v57
	v_mul_f32_e32 v158, 0xbfb8aa3b, v58
	v_mul_f32_e32 v159, 0xbfb8aa3b, v59
	v_exp_f32_e32 v152, v152
	v_exp_f32_e32 v153, v153
	v_exp_f32_e32 v154, v154
	v_exp_f32_e32 v155, v155
	v_exp_f32_e32 v156, v156
	v_exp_f32_e32 v157, v157
	v_exp_f32_e32 v158, v158
	v_exp_f32_e32 v159, v159
	v_add_f32_e32 v152, 1.0, v152
	v_add_f32_e32 v153, 1.0, v153
	v_add_f32_e32 v154, 1.0, v154
	v_add_f32_e32 v155, 1.0, v155
	v_add_f32_e32 v156, 1.0, v156
	v_add_f32_e32 v157, 1.0, v157
	v_add_f32_e32 v158, 1.0, v158
	v_add_f32_e32 v159, 1.0, v159
	v_rcp_f32_e32 v152, v152
	v_rcp_f32_e32 v153, v153
	v_rcp_f32_e32 v154, v154
	v_rcp_f32_e32 v155, v155
	v_rcp_f32_e32 v156, v156
	v_rcp_f32_e32 v157, v157
	v_rcp_f32_e32 v158, v158
	v_rcp_f32_e32 v159, v159
	v_pk_mul_f32 v[60:61], v[60:61], v[152:153]
	v_pk_mul_f32 v[62:63], v[62:63], v[154:155]
	v_pk_mul_f32 v[56:57], v[56:57], v[156:157]
	v_pk_mul_f32 v[58:59], v[58:59], v[158:159]
	v_pk_mul_f32 v[52:53], v[52:53], v[60:61]
	v_pk_mul_f32 v[54:55], v[54:55], v[62:63]
	v_pk_mul_f32 v[48:49], v[48:49], v[56:57]
	v_pk_mul_f32 v[50:51], v[50:51], v[58:59]
	v_cvt_pk_bf16_f32 v172, v52, v53
	v_cvt_pk_bf16_f32 v173, v54, v55
	v_cvt_pk_bf16_f32 v174, v48, v49
	v_cvt_pk_bf16_f32 v175, v50, v51
	global_store_dwordx4 v[150:151], v[172:175], off
	v_lshl_add_u64 v[150:151], v[150:151], 0, s[16:17]
	v_mov_b32_e32 v146, v187
	v_mov_b32_e32 v147, v187
	v_pk_mul_f32 v[44:45], v[44:45], v[146:147]
	v_pk_mul_f32 v[46:47], v[46:47], v[146:147]
	v_pk_mul_f32 v[40:41], v[40:41], v[146:147]
	v_pk_mul_f32 v[42:43], v[42:43], v[146:147]
	v_pk_mul_f32 v[36:37], v[36:37], v[146:147]
	v_pk_mul_f32 v[38:39], v[38:39], v[146:147]
	v_pk_mul_f32 v[32:33], v[32:33], v[146:147]
	v_pk_mul_f32 v[34:35], v[34:35], v[146:147]
	v_mul_f32_e32 v152, 0xbfb8aa3b, v44
	v_mul_f32_e32 v153, 0xbfb8aa3b, v45
	v_mul_f32_e32 v154, 0xbfb8aa3b, v46
	v_mul_f32_e32 v155, 0xbfb8aa3b, v47
	v_mul_f32_e32 v156, 0xbfb8aa3b, v40
	v_mul_f32_e32 v157, 0xbfb8aa3b, v41
	v_mul_f32_e32 v158, 0xbfb8aa3b, v42
	v_mul_f32_e32 v159, 0xbfb8aa3b, v43
	v_exp_f32_e32 v152, v152
	v_exp_f32_e32 v153, v153
	v_exp_f32_e32 v154, v154
	v_exp_f32_e32 v155, v155
	v_exp_f32_e32 v156, v156
	v_exp_f32_e32 v157, v157
	v_exp_f32_e32 v158, v158
	v_exp_f32_e32 v159, v159
	v_add_f32_e32 v152, 1.0, v152
	v_add_f32_e32 v153, 1.0, v153
	v_add_f32_e32 v154, 1.0, v154
	v_add_f32_e32 v155, 1.0, v155
	v_add_f32_e32 v156, 1.0, v156
	v_add_f32_e32 v157, 1.0, v157
; __device__ __forceinline__ unsigned cvt_pk_bf16(float lo, float hi) { unsigned r; asm volatile("v_cvt_pk_bf16_f32 %0, %1, %2" : "=v"(r) : "v"(lo), "v"(hi)); return r; }
; __device__ __forceinline__ float sigm(float x) { return __builtin_amdgcn_rcpf(1.0f + __builtin_amdgcn_exp2f(-1.4426950408889634f * x)); }
;     __device__ __forceinline__ void operator()(const f32x4 (&acc)[2][2][4][2], const Unit& u, int wr, int wc, int fr, int fq) const {
;     ...
;                     bf16_t* rowp = base + (size_t)(row0 + ai * HALF + m * 16) * ld + col0;
;                     const float rr = use_rs ? rsp[row0 + ai * HALF + m * 16] : 1.f;
;                     f32x4 a0 = acc[ai][0][m][0] * rr, a1 = acc[ai][0][m][1] * rr; const f32x4 b0 = acc[ai][1][m][0] * rr, b1 = acc[ai][1][m][1] * rr;
;                     if (k == EK_SWIGLU) {
; #pragma unroll
;                         for (int i = 0; i < 4; ++i) { a0[i] = a0[i] * sigm(a0[i]); a1[i] = a1[i] * sigm(a1[i]); }
;                     }
;                     const f32x4 v0 = a0 * b0, v1 = a1 * b1;
;                     u32x4e w; w.x = cvt_pk_bf16(v0[0], v0[1]); w.y = cvt_pk_bf16(v0[2], v0[3]); w.z = cvt_pk_bf16(v1[0], v1[1]); w.w = cvt_pk_bf16(v1[2], v1[3]);
;                     *(u32x4e*)rowp = w;
	v_add_f32_e32 v158, 1.0, v158
	v_add_f32_e32 v159, 1.0, v159
	v_rcp_f32_e32 v152, v152
	v_rcp_f32_e32 v153, v153
	v_rcp_f32_e32 v154, v154
	v_rcp_f32_e32 v155, v155
	v_rcp_f32_e32 v156, v156
	v_rcp_f32_e32 v157, v157
	v_rcp_f32_e32 v158, v158
	v_rcp_f32_e32 v159, v159
	v_pk_mul_f32 v[44:45], v[44:45], v[152:153]
	v_pk_mul_f32 v[46:47], v[46:47], v[154:155]
	v_pk_mul_f32 v[40:41], v[40:41], v[156:157]
	v_pk_mul_f32 v[42:43], v[42:43], v[158:159]
	v_pk_mul_f32 v[36:37], v[36:37], v[44:45]
	v_pk_mul_f32 v[38:39], v[38:39], v[46:47]
	v_pk_mul_f32 v[32:33], v[32:33], v[40:41]
	v_pk_mul_f32 v[34:35], v[34:35], v[42:43]
	v_cvt_pk_bf16_f32 v176, v36, v37
	v_cvt_pk_bf16_f32 v177, v38, v39
	v_cvt_pk_bf16_f32 v178, v32, v33
	v_cvt_pk_bf16_f32 v179, v34, v35
	global_store_dwordx4 v[150:151], v[176:179], off
	v_lshl_add_u64 v[150:151], v[150:151], 0, s[16:17]
	v_mov_b32_e32 v146, v188
	v_mov_b32_e32 v147, v188
	v_pk_mul_f32 v[28:29], v[28:29], v[146:147]
	v_pk_mul_f32 v[30:31], v[30:31], v[146:147]
	v_pk_mul_f32 v[24:25], v[24:25], v[146:147]
	v_pk_mul_f32 v[26:27], v[26:27], v[146:147]
	v_pk_mul_f32 v[20:21], v[20:21], v[146:147]
	v_pk_mul_f32 v[22:23], v[22:23], v[146:147]
	v_pk_mul_f32 v[16:17], v[16:17], v[146:147]
	v_pk_mul_f32 v[18:19], v[18:19], v[146:147]
	v_mul_f32_e32 v152, 0xbfb8aa3b, v28
	v_mul_f32_e32 v153, 0xbfb8aa3b, v29
	v_mul_f32_e32 v154, 0xbfb8aa3b, v30
	v_mul_f32_e32 v155, 0xbfb8aa3b, v31
	v_mul_f32_e32 v156, 0xbfb8aa3b, v24
	v_mul_f32_e32 v157, 0xbfb8aa3b, v25
	v_mul_f32_e32 v158, 0xbfb8aa3b, v26
	v_mul_f32_e32 v159, 0xbfb8aa3b, v27
	v_exp_f32_e32 v152, v152
	v_exp_f32_e32 v153, v153
	v_exp_f32_e32 v154, v154
	v_exp_f32_e32 v155, v155
	v_exp_f32_e32 v156, v156
	v_exp_f32_e32 v157, v157
	v_exp_f32_e32 v158, v158
	v_exp_f32_e32 v159, v159
	v_add_f32_e32 v152, 1.0, v152
	v_add_f32_e32 v153, 1.0, v153
	v_add_f32_e32 v154, 1.0, v154
	v_add_f32_e32 v155, 1.0, v155
	v_add_f32_e32 v156, 1.0, v156
	v_add_f32_e32 v157, 1.0, v157
	v_add_f32_e32 v158, 1.0, v158
	v_add_f32_e32 v159, 1.0, v159
	v_rcp_f32_e32 v152, v152
	v_rcp_f32_e32 v153, v153
	v_rcp_f32_e32 v154, v154
	v_rcp_f32_e32 v155, v155
	v_rcp_f32_e32 v156, v156
	v_rcp_f32_e32 v157, v157
	v_rcp_f32_e32 v158, v158
	v_rcp_f32_e32 v159, v159
	v_pk_mul_f32 v[28:29], v[28:29], v[152:153]
	v_pk_mul_f32 v[30:31], v[30:31], v[154:155]
	v_pk_mul_f32 v[24:25], v[24:25], v[156:157]
	v_pk_mul_f32 v[26:27], v[26:27], v[158:159]
	v_pk_mul_f32 v[20:21], v[20:21], v[28:29]
	v_pk_mul_f32 v[22:23], v[22:23], v[30:31]
	v_pk_mul_f32 v[16:17], v[16:17], v[24:25]
	v_pk_mul_f32 v[18:19], v[18:19], v[26:27]
	v_cvt_pk_bf16_f32 v172, v20, v21
	v_cvt_pk_bf16_f32 v173, v22, v23
	v_cvt_pk_bf16_f32 v174, v16, v17
	v_cvt_pk_bf16_f32 v175, v18, v19
	global_store_dwordx4 v[150:151], v[172:175], off
	v_lshl_add_u64 v[150:151], v[150:151], 0, s[16:17]
	v_mov_b32_e32 v146, v189
	v_mov_b32_e32 v147, v189
	v_pk_mul_f32 v[12:13], v[12:13], v[146:147]
	v_pk_mul_f32 v[14:15], v[14:15], v[146:147]
	v_pk_mul_f32 v[8:9], v[8:9], v[146:147]
	v_pk_mul_f32 v[10:11], v[10:11], v[146:147]
	v_pk_mul_f32 v[4:5], v[4:5], v[146:147]
	v_pk_mul_f32 v[6:7], v[6:7], v[146:147]
	v_pk_mul_f32 v[0:1], v[0:1], v[146:147]
	v_pk_mul_f32 v[2:3], v[2:3], v[146:147]
	v_mul_f32_e32 v152, 0xbfb8aa3b, v12
	v_mul_f32_e32 v153, 0xbfb8aa3b, v13
	v_mul_f32_e32 v154, 0xbfb8aa3b, v14
	v_mul_f32_e32 v155, 0xbfb8aa3b, v15
	v_mul_f32_e32 v156, 0xbfb8aa3b, v8
	v_mul_f32_e32 v157, 0xbfb8aa3b, v9
	v_mul_f32_e32 v158, 0xbfb8aa3b, v10
	v_mul_f32_e32 v159, 0xbfb8aa3b, v11
	v_exp_f32_e32 v152, v152
	v_exp_f32_e32 v153, v153
	v_exp_f32_e32 v154, v154
	v_exp_f32_e32 v155, v155
	v_exp_f32_e32 v156, v156
	v_exp_f32_e32 v157, v157
	v_exp_f32_e32 v158, v158
	v_exp_f32_e32 v159, v159
	v_add_f32_e32 v152, 1.0, v152
	v_add_f32_e32 v153, 1.0, v153
	v_add_f32_e32 v154, 1.0, v154
	v_add_f32_e32 v155, 1.0, v155
	v_add_f32_e32 v156, 1.0, v156
	v_add_f32_e32 v157, 1.0, v157
	v_add_f32_e32 v158, 1.0, v158
	v_add_f32_e32 v159, 1.0, v159
	v_rcp_f32_e32 v152, v152
	v_rcp_f32_e32 v153, v153
	v_rcp_f32_e32 v154, v154
	v_rcp_f32_e32 v155, v155
	v_rcp_f32_e32 v156, v156
	v_rcp_f32_e32 v157, v157
	v_rcp_f32_e32 v158, v158
	v_rcp_f32_e32 v159, v159
	v_pk_mul_f32 v[12:13], v[12:13], v[152:153]
	v_pk_mul_f32 v[14:15], v[14:15], v[154:155]
	v_pk_mul_f32 v[8:9], v[8:9], v[156:157]
	v_pk_mul_f32 v[10:11], v[10:11], v[158:159]
	v_pk_mul_f32 v[4:5], v[4:5], v[12:13]
	v_pk_mul_f32 v[6:7], v[6:7], v[14:15]
	v_pk_mul_f32 v[0:1], v[0:1], v[8:9]
	v_pk_mul_f32 v[2:3], v[2:3], v[10:11]
	v_cvt_pk_bf16_f32 v176, v4, v5
	v_cvt_pk_bf16_f32 v177, v6, v7
	v_cvt_pk_bf16_f32 v178, v0, v1
	v_cvt_pk_bf16_f32 v179, v2, v3
	global_store_dwordx4 v[150:151], v[176:179], off
	s_branch .LBB0_967
; __device__ __forceinline__ unsigned cvt_pk_bf16(float lo, float hi) { unsigned r; asm volatile("v_cvt_pk_bf16_f32 %0, %1, %2" : "=v"(r) : "v"(lo), "v"(hi)); return r; }
; __device__ __forceinline__ float sigm(float x) { return __builtin_amdgcn_rcpf(1.0f + __builtin_amdgcn_exp2f(-1.4426950408889634f * x)); }
;     __device__ __forceinline__ void operator()(const f32x4 (&acc)[2][2][4][2], const Unit& u, int wr, int wc, int fr, int fq) const {
;     ...
;             for (int ai = 0; ai < 2; ++ai)
; #pragma unroll
;                 for (int m = 0; m < 4; ++m) {
;                     const size_t roff = (size_t)(row0 + ai * HALF + m * 16) * ld + col0;
;                     const float rr = use_rs ? rsp[row0 + ai * HALF + m * 16] : 1.f;
; #pragma unroll
;                     for (int bj = 0; bj < 2; ++bj) {
;                         f32x4 v0 = acc[ai][bj][m][0], v1 = acc[ai][bj][m][1];
;                         const size_t off = roff + bj * HALF;
;                         if (k == EK_PLAIN) { v0 = v0 * (sc * rr); v1 = v1 * (sc * rr); }
;                         else if (k == EK_SIGMOID) {
; #pragma unroll
;                             for (int i = 0; i < 4; ++i) { v0[i] = sigm(v0[i] * rr); v1[i] = sigm(v1[i] * rr); }
;                         } else if (k == EK_GATE) {
;                             const u32x4e g = *(const u32x4e*)(aux1 + off);
;                             v0[0] *= bflo(g.x); v0[1] *= bfhi(g.x); v0[2] *= bflo(g.y); v0[3] *= bfhi(g.y);
;                             v1[0] *= bflo(g.z); v1[1] *= bfhi(g.z); v1[2] *= bflo(g.w); v1[3] *= bfhi(g.w);
;                         } else {
;                             const u32x4e y = *(const u32x4e*)(aux1 + off); const u32x4e g = *(const u32x4e*)(aux2 + off);
;                             v0[0] = bflo(y.x) + bflo(g.x) * v0[0]; v0[1] = bfhi(y.x) + bfhi(g.x) * v0[1]; v0[2] = bflo(y.y) + bflo(g.y) * v0[2]; v0[3] = bfhi(y.y) + bfhi(g.y) * v0[3];
;                             v1[0] = bflo(y.z) + bflo(g.z) * v1[0]; v1[1] = bfhi(y.z) + bfhi(g.z) * v1[1]; v1[2] = bflo(y.w) + bflo(g.w) * v1[2]; v1[3] = bfhi(y.w) + bfhi(g.w) * v1[3];
;                         }
;                         u32x4e w; w.x = cvt_pk_bf16(v0[0], v0[1]); w.y = cvt_pk_bf16(v0[2], v0[3]); w.z = cvt_pk_bf16(v1[0], v1[1]); w.w = cvt_pk_bf16(v1[2], v1[3]);
;                         *(u32x4e*)(base + off) = w;
.Lepi_sig_fast:
	v_mad_i64_i32 v[148:149], s[8:9], s27, v140, v[142:143]
	s_lshl_b32 s16, s27, 5
	s_mov_b32 s17, 0
	s_mul_i32 s30, s27, 0xa0
	s_mov_b32 s31, 0
	v_lshl_add_u64 v[150:151], v[148:149], 1, s[40:41]
	v_mul_f32_e32 v126, v126, v182
	v_mul_f32_e32 v127, v127, v182
	v_mul_f32_e32 v128, v128, v182
	v_mul_f32_e32 v129, v129, v182
	v_mul_f32_e32 v122, v122, v182
	v_mul_f32_e32 v123, v123, v182
	v_mul_f32_e32 v124, v124, v182
	v_mul_f32_e32 v125, v125, v182
	v_mul_f32_e32 v126, 0xbfb8aa3b, v126
	v_mul_f32_e32 v127, 0xbfb8aa3b, v127
	v_mul_f32_e32 v128, 0xbfb8aa3b, v128
	v_mul_f32_e32 v129, 0xbfb8aa3b, v129
	v_mul_f32_e32 v122, 0xbfb8aa3b, v122
	v_mul_f32_e32 v123, 0xbfb8aa3b, v123
	v_mul_f32_e32 v124, 0xbfb8aa3b, v124
	v_mul_f32_e32 v125, 0xbfb8aa3b, v125
	v_exp_f32_e32 v126, v126
	v_exp_f32_e32 v127, v127
	v_exp_f32_e32 v128, v128
	v_exp_f32_e32 v129, v129
	v_exp_f32_e32 v122, v122
	v_exp_f32_e32 v123, v123
	v_exp_f32_e32 v124, v124
	v_exp_f32_e32 v125, v125
	v_add_f32_e32 v126, 1.0, v126
	v_add_f32_e32 v127, 1.0, v127
	v_add_f32_e32 v128, 1.0, v128
	v_add_f32_e32 v129, 1.0, v129
	v_add_f32_e32 v122, 1.0, v122
	v_add_f32_e32 v123, 1.0, v123
	v_add_f32_e32 v124, 1.0, v124
	v_add_f32_e32 v125, 1.0, v125
	v_rcp_f32_e32 v126, v126
	v_rcp_f32_e32 v127, v127
	v_rcp_f32_e32 v128, v128
	v_rcp_f32_e32 v129, v129
	v_rcp_f32_e32 v122, v122
	v_rcp_f32_e32 v123, v123
	v_rcp_f32_e32 v124, v124
	v_rcp_f32_e32 v125, v125
	s_nop 0
	v_cvt_pk_bf16_f32 v172, v126, v127
	v_cvt_pk_bf16_f32 v173, v128, v129
	v_cvt_pk_bf16_f32 v174, v122, v123
	v_cvt_pk_bf16_f32 v175, v124, v125
	global_store_dwordx4 v[150:151], v[172:175], off
	v_mul_f32_e32 v118, v118, v182
	v_mul_f32_e32 v119, v119, v182
	v_mul_f32_e32 v120, v120, v182
	v_mul_f32_e32 v121, v121, v182
	v_mul_f32_e32 v114, v114, v182
	v_mul_f32_e32 v115, v115, v182
	v_mul_f32_e32 v116, v116, v182
	v_mul_f32_e32 v117, v117, v182
	v_mul_f32_e32 v118, 0xbfb8aa3b, v118
	v_mul_f32_e32 v119, 0xbfb8aa3b, v119
	v_mul_f32_e32 v120, 0xbfb8aa3b, v120
	v_mul_f32_e32 v121, 0xbfb8aa3b, v121
	v_mul_f32_e32 v114, 0xbfb8aa3b, v114
	v_mul_f32_e32 v115, 0xbfb8aa3b, v115
	v_mul_f32_e32 v116, 0xbfb8aa3b, v116
	v_mul_f32_e32 v117, 0xbfb8aa3b, v117
	v_exp_f32_e32 v118, v118
	v_exp_f32_e32 v119, v119
	v_exp_f32_e32 v120, v120
	v_exp_f32_e32 v121, v121
	v_exp_f32_e32 v114, v114
	v_exp_f32_e32 v115, v115
	v_exp_f32_e32 v116, v116
	v_exp_f32_e32 v117, v117
	v_add_f32_e32 v118, 1.0, v118
	v_add_f32_e32 v119, 1.0, v119
	v_add_f32_e32 v120, 1.0, v120
	v_add_f32_e32 v121, 1.0, v121
	v_add_f32_e32 v114, 1.0, v114
	v_add_f32_e32 v115, 1.0, v115
	v_add_f32_e32 v116, 1.0, v116
	v_add_f32_e32 v117, 1.0, v117
	v_rcp_f32_e32 v118, v118
	v_rcp_f32_e32 v119, v119
	v_rcp_f32_e32 v120, v120
	v_rcp_f32_e32 v121, v121
	v_rcp_f32_e32 v114, v114
	v_rcp_f32_e32 v115, v115
	v_rcp_f32_e32 v116, v116
	v_rcp_f32_e32 v117, v117
	s_nop 0
	v_cvt_pk_bf16_f32 v176, v118, v119
	v_cvt_pk_bf16_f32 v177, v120, v121
	v_cvt_pk_bf16_f32 v178, v114, v115
	v_cvt_pk_bf16_f32 v179, v116, v117
	global_store_dwordx4 v[150:151], v[176:179], off offset:256
	v_lshl_add_u64 v[150:151], v[150:151], 0, s[16:17]
	v_mul_f32_e32 v110, v110, v183
	v_mul_f32_e32 v111, v111, v183
	v_mul_f32_e32 v112, v112, v183
	v_mul_f32_e32 v113, v113, v183
	v_mul_f32_e32 v106, v106, v183
	v_mul_f32_e32 v107, v107, v183
	v_mul_f32_e32 v108, v108, v183
	v_mul_f32_e32 v109, v109, v183
	v_mul_f32_e32 v110, 0xbfb8aa3b, v110
	v_mul_f32_e32 v111, 0xbfb8aa3b, v111
	v_mul_f32_e32 v112, 0xbfb8aa3b, v112
	v_mul_f32_e32 v113, 0xbfb8aa3b, v113
	v_mul_f32_e32 v106, 0xbfb8aa3b, v106
	v_mul_f32_e32 v107, 0xbfb8aa3b, v107
	v_mul_f32_e32 v108, 0xbfb8aa3b, v108
	v_mul_f32_e32 v109, 0xbfb8aa3b, v109
	v_exp_f32_e32 v110, v110
	v_exp_f32_e32 v111, v111
	v_exp_f32_e32 v112, v112
	v_exp_f32_e32 v113, v113
	v_exp_f32_e32 v106, v106
	v_exp_f32_e32 v107, v107
	v_exp_f32_e32 v108, v108
	v_exp_f32_e32 v109, v109
	v_add_f32_e32 v110, 1.0, v110
	v_add_f32_e32 v111, 1.0, v111
	v_add_f32_e32 v112, 1.0, v112
	v_add_f32_e32 v113, 1.0, v113
	v_add_f32_e32 v106, 1.0, v106
	v_add_f32_e32 v107, 1.0, v107
	v_add_f32_e32 v108, 1.0, v108
	v_add_f32_e32 v109, 1.0, v109
	v_rcp_f32_e32 v110, v110
	v_rcp_f32_e32 v111, v111
	v_rcp_f32_e32 v112, v112
	v_rcp_f32_e32 v113, v113
	v_rcp_f32_e32 v106, v106
	v_rcp_f32_e32 v107, v107
	v_rcp_f32_e32 v108, v108
	v_rcp_f32_e32 v109, v109
	s_nop 0
	v_cvt_pk_bf16_f32 v172, v110, v111
	v_cvt_pk_bf16_f32 v173, v112, v113
	v_cvt_pk_bf16_f32 v174, v106, v107
	v_cvt_pk_bf16_f32 v175, v108, v109
	global_store_dwordx4 v[150:151], v[172:175], off
	v_mul_f32_e32 v102, v102, v183
	v_mul_f32_e32 v103, v103, v183
	v_mul_f32_e32 v104, v104, v183
	v_mul_f32_e32 v105, v105, v183
	v_mul_f32_e32 v98, v98, v183
	v_mul_f32_e32 v99, v99, v183
	v_mul_f32_e32 v100, v100, v183
	v_mul_f32_e32 v101, v101, v183
	v_mul_f32_e32 v102, 0xbfb8aa3b, v102
	v_mul_f32_e32 v103, 0xbfb8aa3b, v103
	v_mul_f32_e32 v104, 0xbfb8aa3b, v104
	v_mul_f32_e32 v105, 0xbfb8aa3b, v105
	v_mul_f32_e32 v98, 0xbfb8aa3b, v98
	v_mul_f32_e32 v99, 0xbfb8aa3b, v99
	v_mul_f32_e32 v100, 0xbfb8aa3b, v100
	v_mul_f32_e32 v101, 0xbfb8aa3b, v101
	v_exp_f32_e32 v102, v102
	v_exp_f32_e32 v103, v103
	v_exp_f32_e32 v104, v104
	v_exp_f32_e32 v105, v105
	v_exp_f32_e32 v98, v98
	v_exp_f32_e32 v99, v99
	v_exp_f32_e32 v100, v100
	v_exp_f32_e32 v101, v101
	v_add_f32_e32 v102, 1.0, v102
	v_add_f32_e32 v103, 1.0, v103
	v_add_f32_e32 v104, 1.0, v104
	v_add_f32_e32 v105, 1.0, v105
	v_add_f32_e32 v98, 1.0, v98
	v_add_f32_e32 v99, 1.0, v99
	v_add_f32_e32 v100, 1.0, v100
	v_add_f32_e32 v101, 1.0, v101
	v_rcp_f32_e32 v102, v102
	v_rcp_f32_e32 v103, v103
	v_rcp_f32_e32 v104, v104
; __device__ __forceinline__ unsigned cvt_pk_bf16(float lo, float hi) { unsigned r; asm volatile("v_cvt_pk_bf16_f32 %0, %1, %2" : "=v"(r) : "v"(lo), "v"(hi)); return r; }
; __device__ __forceinline__ float sigm(float x) { return __builtin_amdgcn_rcpf(1.0f + __builtin_amdgcn_exp2f(-1.4426950408889634f * x)); }
;     __device__ __forceinline__ void operator()(const f32x4 (&acc)[2][2][4][2], const Unit& u, int wr, int wc, int fr, int fq) const {
;     ...
;             for (int ai = 0; ai < 2; ++ai)
; #pragma unroll
;                 for (int m = 0; m < 4; ++m) {
;                     const size_t roff = (size_t)(row0 + ai * HALF + m * 16) * ld + col0;
;                     const float rr = use_rs ? rsp[row0 + ai * HALF + m * 16] : 1.f;
; #pragma unroll
;                     for (int bj = 0; bj < 2; ++bj) {
;                         f32x4 v0 = acc[ai][bj][m][0], v1 = acc[ai][bj][m][1];
;                         const size_t off = roff + bj * HALF;
;                         if (k == EK_PLAIN) { v0 = v0 * (sc * rr); v1 = v1 * (sc * rr); }
;                         else if (k == EK_SIGMOID) {
; #pragma unroll
;                             for (int i = 0; i < 4; ++i) { v0[i] = sigm(v0[i] * rr); v1[i] = sigm(v1[i] * rr); }
;                         } else if (k == EK_GATE) {
;                             const u32x4e g = *(const u32x4e*)(aux1 + off);
;                             v0[0] *= bflo(g.x); v0[1] *= bfhi(g.x); v0[2] *= bflo(g.y); v0[3] *= bfhi(g.y);
;                             v1[0] *= bflo(g.z); v1[1] *= bfhi(g.z); v1[2] *= bflo(g.w); v1[3] *= bfhi(g.w);
;                         } else {
;                             const u32x4e y = *(const u32x4e*)(aux1 + off); const u32x4e g = *(const u32x4e*)(aux2 + off);
;                             v0[0] = bflo(y.x) + bflo(g.x) * v0[0]; v0[1] = bfhi(y.x) + bfhi(g.x) * v0[1]; v0[2] = bflo(y.y) + bflo(g.y) * v0[2]; v0[3] = bfhi(y.y) + bfhi(g.y) * v0[3];
;                             v1[0] = bflo(y.z) + bflo(g.z) * v1[0]; v1[1] = bfhi(y.z) + bfhi(g.z) * v1[1]; v1[2] = bflo(y.w) + bflo(g.w) * v1[2]; v1[3] = bfhi(y.w) + bfhi(g.w) * v1[3];
;                         }
;                         u32x4e w; w.x = cvt_pk_bf16(v0[0], v0[1]); w.y = cvt_pk_bf16(v0[2], v0[3]); w.z = cvt_pk_bf16(v1[0], v1[1]); w.w = cvt_pk_bf16(v1[2], v1[3]);
;                         *(u32x4e*)(base + off) = w;
	v_rcp_f32_e32 v105, v105
	v_rcp_f32_e32 v98, v98
	v_rcp_f32_e32 v99, v99
	v_rcp_f32_e32 v100, v100
	v_rcp_f32_e32 v101, v101
	s_nop 0
	v_cvt_pk_bf16_f32 v176, v102, v103
	v_cvt_pk_bf16_f32 v177, v104, v105
	v_cvt_pk_bf16_f32 v178, v98, v99
	v_cvt_pk_bf16_f32 v179, v100, v101
	global_store_dwordx4 v[150:151], v[176:179], off offset:256
	v_lshl_add_u64 v[150:151], v[150:151], 0, s[16:17]
	v_mul_f32_e32 v94, v94, v184
	v_mul_f32_e32 v95, v95, v184
	v_mul_f32_e32 v96, v96, v184
	v_mul_f32_e32 v97, v97, v184
	v_mul_f32_e32 v90, v90, v184
	v_mul_f32_e32 v91, v91, v184
	v_mul_f32_e32 v92, v92, v184
	v_mul_f32_e32 v93, v93, v184
	v_mul_f32_e32 v94, 0xbfb8aa3b, v94
	v_mul_f32_e32 v95, 0xbfb8aa3b, v95
	v_mul_f32_e32 v96, 0xbfb8aa3b, v96
	v_mul_f32_e32 v97, 0xbfb8aa3b, v97
	v_mul_f32_e32 v90, 0xbfb8aa3b, v90
	v_mul_f32_e32 v91, 0xbfb8aa3b, v91
	v_mul_f32_e32 v92, 0xbfb8aa3b, v92
	v_mul_f32_e32 v93, 0xbfb8aa3b, v93
	v_exp_f32_e32 v94, v94
	v_exp_f32_e32 v95, v95
	v_exp_f32_e32 v96, v96
	v_exp_f32_e32 v97, v97
	v_exp_f32_e32 v90, v90
	v_exp_f32_e32 v91, v91
	v_exp_f32_e32 v92, v92
	v_exp_f32_e32 v93, v93
	v_add_f32_e32 v94, 1.0, v94
	v_add_f32_e32 v95, 1.0, v95
	v_add_f32_e32 v96, 1.0, v96
	v_add_f32_e32 v97, 1.0, v97
	v_add_f32_e32 v90, 1.0, v90
	v_add_f32_e32 v91, 1.0, v91
	v_add_f32_e32 v92, 1.0, v92
	v_add_f32_e32 v93, 1.0, v93
	v_rcp_f32_e32 v94, v94
	v_rcp_f32_e32 v95, v95
	v_rcp_f32_e32 v96, v96
	v_rcp_f32_e32 v97, v97
	v_rcp_f32_e32 v90, v90
	v_rcp_f32_e32 v91, v91
	v_rcp_f32_e32 v92, v92
	v_rcp_f32_e32 v93, v93
	s_nop 0
	v_cvt_pk_bf16_f32 v172, v94, v95
	v_cvt_pk_bf16_f32 v173, v96, v97
	v_cvt_pk_bf16_f32 v174, v90, v91
	v_cvt_pk_bf16_f32 v175, v92, v93
	global_store_dwordx4 v[150:151], v[172:175], off
	v_mul_f32_e32 v86, v86, v184
	v_mul_f32_e32 v87, v87, v184
	v_mul_f32_e32 v88, v88, v184
	v_mul_f32_e32 v89, v89, v184
	v_mul_f32_e32 v82, v82, v184
	v_mul_f32_e32 v83, v83, v184
	v_mul_f32_e32 v84, v84, v184
	v_mul_f32_e32 v85, v85, v184
	v_mul_f32_e32 v86, 0xbfb8aa3b, v86
	v_mul_f32_e32 v87, 0xbfb8aa3b, v87
	v_mul_f32_e32 v88, 0xbfb8aa3b, v88
	v_mul_f32_e32 v89, 0xbfb8aa3b, v89
	v_mul_f32_e32 v82, 0xbfb8aa3b, v82
	v_mul_f32_e32 v83, 0xbfb8aa3b, v83
	v_mul_f32_e32 v84, 0xbfb8aa3b, v84
	v_mul_f32_e32 v85, 0xbfb8aa3b, v85
	v_exp_f32_e32 v86, v86
	v_exp_f32_e32 v87, v87
	v_exp_f32_e32 v88, v88
	v_exp_f32_e32 v89, v89
	v_exp_f32_e32 v82, v82
	v_exp_f32_e32 v83, v83
	v_exp_f32_e32 v84, v84
	v_exp_f32_e32 v85, v85
	v_add_f32_e32 v86, 1.0, v86
	v_add_f32_e32 v87, 1.0, v87
	v_add_f32_e32 v88, 1.0, v88
	v_add_f32_e32 v89, 1.0, v89
	v_add_f32_e32 v82, 1.0, v82
	v_add_f32_e32 v83, 1.0, v83
	v_add_f32_e32 v84, 1.0, v84
	v_add_f32_e32 v85, 1.0, v85
	v_rcp_f32_e32 v86, v86
	v_rcp_f32_e32 v87, v87
	v_rcp_f32_e32 v88, v88
	v_rcp_f32_e32 v89, v89
	v_rcp_f32_e32 v82, v82
	v_rcp_f32_e32 v83, v83
	v_rcp_f32_e32 v84, v84
	v_rcp_f32_e32 v85, v85
	s_nop 0
	v_cvt_pk_bf16_f32 v176, v86, v87
	v_cvt_pk_bf16_f32 v177, v88, v89
	v_cvt_pk_bf16_f32 v178, v82, v83
	v_cvt_pk_bf16_f32 v179, v84, v85
	global_store_dwordx4 v[150:151], v[176:179], off offset:256
	v_lshl_add_u64 v[150:151], v[150:151], 0, s[16:17]
	v_mul_f32_e32 v78, v78, v185
	v_mul_f32_e32 v79, v79, v185
	v_mul_f32_e32 v80, v80, v185
	v_mul_f32_e32 v81, v81, v185
	v_mul_f32_e32 v74, v74, v185
	v_mul_f32_e32 v75, v75, v185
	v_mul_f32_e32 v76, v76, v185
	v_mul_f32_e32 v77, v77, v185
	v_mul_f32_e32 v78, 0xbfb8aa3b, v78
	v_mul_f32_e32 v79, 0xbfb8aa3b, v79
	v_mul_f32_e32 v80, 0xbfb8aa3b, v80
	v_mul_f32_e32 v81, 0xbfb8aa3b, v81
	v_mul_f32_e32 v74, 0xbfb8aa3b, v74
	v_mul_f32_e32 v75, 0xbfb8aa3b, v75
	v_mul_f32_e32 v76, 0xbfb8aa3b, v76
	v_mul_f32_e32 v77, 0xbfb8aa3b, v77
	v_exp_f32_e32 v78, v78
	v_exp_f32_e32 v79, v79
	v_exp_f32_e32 v80, v80
	v_exp_f32_e32 v81, v81
	v_exp_f32_e32 v74, v74
	v_exp_f32_e32 v75, v75
	v_exp_f32_e32 v76, v76
	v_exp_f32_e32 v77, v77
	v_add_f32_e32 v78, 1.0, v78
	v_add_f32_e32 v79, 1.0, v79
	v_add_f32_e32 v80, 1.0, v80
	v_add_f32_e32 v81, 1.0, v81
	v_add_f32_e32 v74, 1.0, v74
	v_add_f32_e32 v75, 1.0, v75
	v_add_f32_e32 v76, 1.0, v76
	v_add_f32_e32 v77, 1.0, v77
	v_rcp_f32_e32 v78, v78
	v_rcp_f32_e32 v79, v79
	v_rcp_f32_e32 v80, v80
	v_rcp_f32_e32 v81, v81
	v_rcp_f32_e32 v74, v74
	v_rcp_f32_e32 v75, v75
	v_rcp_f32_e32 v76, v76
	v_rcp_f32_e32 v77, v77
	s_nop 0
	v_cvt_pk_bf16_f32 v172, v78, v79
	v_cvt_pk_bf16_f32 v173, v80, v81
	v_cvt_pk_bf16_f32 v174, v74, v75
	v_cvt_pk_bf16_f32 v175, v76, v77
	global_store_dwordx4 v[150:151], v[172:175], off
	v_mul_f32_e32 v70, v70, v185
	v_mul_f32_e32 v71, v71, v185
	v_mul_f32_e32 v72, v72, v185
	v_mul_f32_e32 v73, v73, v185
	v_mul_f32_e32 v66, v66, v185
	v_mul_f32_e32 v67, v67, v185
	v_mul_f32_e32 v68, v68, v185
	v_mul_f32_e32 v69, v69, v185
	v_mul_f32_e32 v70, 0xbfb8aa3b, v70
	v_mul_f32_e32 v71, 0xbfb8aa3b, v71
	v_mul_f32_e32 v72, 0xbfb8aa3b, v72
	v_mul_f32_e32 v73, 0xbfb8aa3b, v73
	v_mul_f32_e32 v66, 0xbfb8aa3b, v66
	v_mul_f32_e32 v67, 0xbfb8aa3b, v67
	v_mul_f32_e32 v68, 0xbfb8aa3b, v68
	v_mul_f32_e32 v69, 0xbfb8aa3b, v69
	v_exp_f32_e32 v70, v70
	v_exp_f32_e32 v71, v71
	v_exp_f32_e32 v72, v72
	v_exp_f32_e32 v73, v73
	v_exp_f32_e32 v66, v66
	v_exp_f32_e32 v67, v67
	v_exp_f32_e32 v68, v68
	v_exp_f32_e32 v69, v69
	v_add_f32_e32 v70, 1.0, v70
	v_add_f32_e32 v71, 1.0, v71
	v_add_f32_e32 v72, 1.0, v72
	v_add_f32_e32 v73, 1.0, v73
	v_add_f32_e32 v66, 1.0, v66
	v_add_f32_e32 v67, 1.0, v67
	v_add_f32_e32 v68, 1.0, v68
	v_add_f32_e32 v69, 1.0, v69
	v_rcp_f32_e32 v70, v70
	v_rcp_f32_e32 v71, v71
	v_rcp_f32_e32 v72, v72
	v_rcp_f32_e32 v73, v73
	v_rcp_f32_e32 v66, v66
	v_rcp_f32_e32 v67, v67
	v_rcp_f32_e32 v68, v68
	v_rcp_f32_e32 v69, v69
	s_nop 0
; __device__ __forceinline__ unsigned cvt_pk_bf16(float lo, float hi) { unsigned r; asm volatile("v_cvt_pk_bf16_f32 %0, %1, %2" : "=v"(r) : "v"(lo), "v"(hi)); return r; }
; __device__ __forceinline__ float sigm(float x) { return __builtin_amdgcn_rcpf(1.0f + __builtin_amdgcn_exp2f(-1.4426950408889634f * x)); }
;     __device__ __forceinline__ void operator()(const f32x4 (&acc)[2][2][4][2], const Unit& u, int wr, int wc, int fr, int fq) const {
;     ...
;             for (int ai = 0; ai < 2; ++ai)
; #pragma unroll
;                 for (int m = 0; m < 4; ++m) {
;                     const size_t roff = (size_t)(row0 + ai * HALF + m * 16) * ld + col0;
;                     const float rr = use_rs ? rsp[row0 + ai * HALF + m * 16] : 1.f;
; #pragma unroll
;                     for (int bj = 0; bj < 2; ++bj) {
;                         f32x4 v0 = acc[ai][bj][m][0], v1 = acc[ai][bj][m][1];
;                         const size_t off = roff + bj * HALF;
;                         if (k == EK_PLAIN) { v0 = v0 * (sc * rr); v1 = v1 * (sc * rr); }
;                         else if (k == EK_SIGMOID) {
; #pragma unroll
;                             for (int i = 0; i < 4; ++i) { v0[i] = sigm(v0[i] * rr); v1[i] = sigm(v1[i] * rr); }
;                         } else if (k == EK_GATE) {
;                             const u32x4e g = *(const u32x4e*)(aux1 + off);
;                             v0[0] *= bflo(g.x); v0[1] *= bfhi(g.x); v0[2] *= bflo(g.y); v0[3] *= bfhi(g.y);
;                             v1[0] *= bflo(g.z); v1[1] *= bfhi(g.z); v1[2] *= bflo(g.w); v1[3] *= bfhi(g.w);
;                         } else {
;                             const u32x4e y = *(const u32x4e*)(aux1 + off); const u32x4e g = *(const u32x4e*)(aux2 + off);
;                             v0[0] = bflo(y.x) + bflo(g.x) * v0[0]; v0[1] = bfhi(y.x) + bfhi(g.x) * v0[1]; v0[2] = bflo(y.y) + bflo(g.y) * v0[2]; v0[3] = bfhi(y.y) + bfhi(g.y) * v0[3];
;                             v1[0] = bflo(y.z) + bflo(g.z) * v1[0]; v1[1] = bfhi(y.z) + bfhi(g.z) * v1[1]; v1[2] = bflo(y.w) + bflo(g.w) * v1[2]; v1[3] = bfhi(y.w) + bfhi(g.w) * v1[3];
;                         }
;                         u32x4e w; w.x = cvt_pk_bf16(v0[0], v0[1]); w.y = cvt_pk_bf16(v0[2], v0[3]); w.z = cvt_pk_bf16(v1[0], v1[1]); w.w = cvt_pk_bf16(v1[2], v1[3]);
;                         *(u32x4e*)(base + off) = w;
	v_cvt_pk_bf16_f32 v176, v70, v71
	v_cvt_pk_bf16_f32 v177, v72, v73
	v_cvt_pk_bf16_f32 v178, v66, v67
	v_cvt_pk_bf16_f32 v179, v68, v69
	global_store_dwordx4 v[150:151], v[176:179], off offset:256
	v_lshl_add_u64 v[150:151], v[150:151], 0, s[30:31]
	v_mul_f32_e32 v60, v60, v186
	v_mul_f32_e32 v61, v61, v186
	v_mul_f32_e32 v62, v62, v186
	v_mul_f32_e32 v63, v63, v186
	v_mul_f32_e32 v56, v56, v186
	v_mul_f32_e32 v57, v57, v186
	v_mul_f32_e32 v58, v58, v186
	v_mul_f32_e32 v59, v59, v186
	v_mul_f32_e32 v60, 0xbfb8aa3b, v60
	v_mul_f32_e32 v61, 0xbfb8aa3b, v61
	v_mul_f32_e32 v62, 0xbfb8aa3b, v62
	v_mul_f32_e32 v63, 0xbfb8aa3b, v63
	v_mul_f32_e32 v56, 0xbfb8aa3b, v56
	v_mul_f32_e32 v57, 0xbfb8aa3b, v57
	v_mul_f32_e32 v58, 0xbfb8aa3b, v58
	v_mul_f32_e32 v59, 0xbfb8aa3b, v59
	v_exp_f32_e32 v60, v60
	v_exp_f32_e32 v61, v61
	v_exp_f32_e32 v62, v62
	v_exp_f32_e32 v63, v63
	v_exp_f32_e32 v56, v56
	v_exp_f32_e32 v57, v57
	v_exp_f32_e32 v58, v58
	v_exp_f32_e32 v59, v59
	v_add_f32_e32 v60, 1.0, v60
	v_add_f32_e32 v61, 1.0, v61
	v_add_f32_e32 v62, 1.0, v62
	v_add_f32_e32 v63, 1.0, v63
	v_add_f32_e32 v56, 1.0, v56
	v_add_f32_e32 v57, 1.0, v57
	v_add_f32_e32 v58, 1.0, v58
	v_add_f32_e32 v59, 1.0, v59
	v_rcp_f32_e32 v60, v60
	v_rcp_f32_e32 v61, v61
	v_rcp_f32_e32 v62, v62
	v_rcp_f32_e32 v63, v63
	v_rcp_f32_e32 v56, v56
	v_rcp_f32_e32 v57, v57
	v_rcp_f32_e32 v58, v58
	v_rcp_f32_e32 v59, v59
	s_nop 0
	v_cvt_pk_bf16_f32 v172, v60, v61
	v_cvt_pk_bf16_f32 v173, v62, v63
	v_cvt_pk_bf16_f32 v174, v56, v57
	v_cvt_pk_bf16_f32 v175, v58, v59
	global_store_dwordx4 v[150:151], v[172:175], off
	v_mul_f32_e32 v52, v52, v186
	v_mul_f32_e32 v53, v53, v186
	v_mul_f32_e32 v54, v54, v186
	v_mul_f32_e32 v55, v55, v186
	v_mul_f32_e32 v48, v48, v186
	v_mul_f32_e32 v49, v49, v186
	v_mul_f32_e32 v50, v50, v186
	v_mul_f32_e32 v51, v51, v186
	v_mul_f32_e32 v52, 0xbfb8aa3b, v52
	v_mul_f32_e32 v53, 0xbfb8aa3b, v53
	v_mul_f32_e32 v54, 0xbfb8aa3b, v54
	v_mul_f32_e32 v55, 0xbfb8aa3b, v55
	v_mul_f32_e32 v48, 0xbfb8aa3b, v48
	v_mul_f32_e32 v49, 0xbfb8aa3b, v49
	v_mul_f32_e32 v50, 0xbfb8aa3b, v50
	v_mul_f32_e32 v51, 0xbfb8aa3b, v51
	v_exp_f32_e32 v52, v52
	v_exp_f32_e32 v53, v53
	v_exp_f32_e32 v54, v54
	v_exp_f32_e32 v55, v55
	v_exp_f32_e32 v48, v48
	v_exp_f32_e32 v49, v49
	v_exp_f32_e32 v50, v50
	v_exp_f32_e32 v51, v51
	v_add_f32_e32 v52, 1.0, v52
	v_add_f32_e32 v53, 1.0, v53
	v_add_f32_e32 v54, 1.0, v54
	v_add_f32_e32 v55, 1.0, v55
	v_add_f32_e32 v48, 1.0, v48
	v_add_f32_e32 v49, 1.0, v49
	v_add_f32_e32 v50, 1.0, v50
	v_add_f32_e32 v51, 1.0, v51
	v_rcp_f32_e32 v52, v52
	v_rcp_f32_e32 v53, v53
	v_rcp_f32_e32 v54, v54
	v_rcp_f32_e32 v55, v55
	v_rcp_f32_e32 v48, v48
	v_rcp_f32_e32 v49, v49
	v_rcp_f32_e32 v50, v50
	v_rcp_f32_e32 v51, v51
	s_nop 0
	v_cvt_pk_bf16_f32 v176, v52, v53
	v_cvt_pk_bf16_f32 v177, v54, v55
	v_cvt_pk_bf16_f32 v178, v48, v49
	v_cvt_pk_bf16_f32 v179, v50, v51
	global_store_dwordx4 v[150:151], v[176:179], off offset:256
	v_lshl_add_u64 v[150:151], v[150:151], 0, s[16:17]
	v_mul_f32_e32 v44, v44, v187
	v_mul_f32_e32 v45, v45, v187
	v_mul_f32_e32 v46, v46, v187
	v_mul_f32_e32 v47, v47, v187
	v_mul_f32_e32 v40, v40, v187
	v_mul_f32_e32 v41, v41, v187
	v_mul_f32_e32 v42, v42, v187
	v_mul_f32_e32 v43, v43, v187
	v_mul_f32_e32 v44, 0xbfb8aa3b, v44
	v_mul_f32_e32 v45, 0xbfb8aa3b, v45
	v_mul_f32_e32 v46, 0xbfb8aa3b, v46
	v_mul_f32_e32 v47, 0xbfb8aa3b, v47
	v_mul_f32_e32 v40, 0xbfb8aa3b, v40
	v_mul_f32_e32 v41, 0xbfb8aa3b, v41
	v_mul_f32_e32 v42, 0xbfb8aa3b, v42
	v_mul_f32_e32 v43, 0xbfb8aa3b, v43
	v_exp_f32_e32 v44, v44
	v_exp_f32_e32 v45, v45
	v_exp_f32_e32 v46, v46
	v_exp_f32_e32 v47, v47
	v_exp_f32_e32 v40, v40
	v_exp_f32_e32 v41, v41
	v_exp_f32_e32 v42, v42
	v_exp_f32_e32 v43, v43
	v_add_f32_e32 v44, 1.0, v44
	v_add_f32_e32 v45, 1.0, v45
	v_add_f32_e32 v46, 1.0, v46
	v_add_f32_e32 v47, 1.0, v47
	v_add_f32_e32 v40, 1.0, v40
	v_add_f32_e32 v41, 1.0, v41
	v_add_f32_e32 v42, 1.0, v42
	v_add_f32_e32 v43, 1.0, v43
	v_rcp_f32_e32 v44, v44
	v_rcp_f32_e32 v45, v45
	v_rcp_f32_e32 v46, v46
	v_rcp_f32_e32 v47, v47
	v_rcp_f32_e32 v40, v40
	v_rcp_f32_e32 v41, v41
	v_rcp_f32_e32 v42, v42
	v_rcp_f32_e32 v43, v43
	s_nop 0
	v_cvt_pk_bf16_f32 v172, v44, v45
	v_cvt_pk_bf16_f32 v173, v46, v47
	v_cvt_pk_bf16_f32 v174, v40, v41
	v_cvt_pk_bf16_f32 v175, v42, v43
	global_store_dwordx4 v[150:151], v[172:175], off
	v_mul_f32_e32 v36, v36, v187
	v_mul_f32_e32 v37, v37, v187
	v_mul_f32_e32 v38, v38, v187
	v_mul_f32_e32 v39, v39, v187
	v_mul_f32_e32 v32, v32, v187
	v_mul_f32_e32 v33, v33, v187
	v_mul_f32_e32 v34, v34, v187
	v_mul_f32_e32 v35, v35, v187
	v_mul_f32_e32 v36, 0xbfb8aa3b, v36
	v_mul_f32_e32 v37, 0xbfb8aa3b, v37
	v_mul_f32_e32 v38, 0xbfb8aa3b, v38
	v_mul_f32_e32 v39, 0xbfb8aa3b, v39
	v_mul_f32_e32 v32, 0xbfb8aa3b, v32
	v_mul_f32_e32 v33, 0xbfb8aa3b, v33
	v_mul_f32_e32 v34, 0xbfb8aa3b, v34
	v_mul_f32_e32 v35, 0xbfb8aa3b, v35
	v_exp_f32_e32 v36, v36
	v_exp_f32_e32 v37, v37
	v_exp_f32_e32 v38, v38
	v_exp_f32_e32 v39, v39
	v_exp_f32_e32 v32, v32
	v_exp_f32_e32 v33, v33
	v_exp_f32_e32 v34, v34
	v_exp_f32_e32 v35, v35
	v_add_f32_e32 v36, 1.0, v36
	v_add_f32_e32 v37, 1.0, v37
	v_add_f32_e32 v38, 1.0, v38
	v_add_f32_e32 v39, 1.0, v39
	v_add_f32_e32 v32, 1.0, v32
	v_add_f32_e32 v33, 1.0, v33
	v_add_f32_e32 v34, 1.0, v34
	v_add_f32_e32 v35, 1.0, v35
	v_rcp_f32_e32 v36, v36
	v_rcp_f32_e32 v37, v37
	v_rcp_f32_e32 v38, v38
	v_rcp_f32_e32 v39, v39
	v_rcp_f32_e32 v32, v32
	v_rcp_f32_e32 v33, v33
	v_rcp_f32_e32 v34, v34
	v_rcp_f32_e32 v35, v35
	s_nop 0
	v_cvt_pk_bf16_f32 v176, v36, v37
	v_cvt_pk_bf16_f32 v177, v38, v39
; __device__ __forceinline__ unsigned cvt_pk_bf16(float lo, float hi) { unsigned r; asm volatile("v_cvt_pk_bf16_f32 %0, %1, %2" : "=v"(r) : "v"(lo), "v"(hi)); return r; }
; __device__ __forceinline__ float sigm(float x) { return __builtin_amdgcn_rcpf(1.0f + __builtin_amdgcn_exp2f(-1.4426950408889634f * x)); }
;     __device__ __forceinline__ void operator()(const f32x4 (&acc)[2][2][4][2], const Unit& u, int wr, int wc, int fr, int fq) const {
;     ...
;             for (int ai = 0; ai < 2; ++ai)
; #pragma unroll
;                 for (int m = 0; m < 4; ++m) {
;                     const size_t roff = (size_t)(row0 + ai * HALF + m * 16) * ld + col0;
;                     const float rr = use_rs ? rsp[row0 + ai * HALF + m * 16] : 1.f;
; #pragma unroll
;                     for (int bj = 0; bj < 2; ++bj) {
;                         f32x4 v0 = acc[ai][bj][m][0], v1 = acc[ai][bj][m][1];
;                         const size_t off = roff + bj * HALF;
;                         if (k == EK_PLAIN) { v0 = v0 * (sc * rr); v1 = v1 * (sc * rr); }
;                         else if (k == EK_SIGMOID) {
; #pragma unroll
;                             for (int i = 0; i < 4; ++i) { v0[i] = sigm(v0[i] * rr); v1[i] = sigm(v1[i] * rr); }
;                         } else if (k == EK_GATE) {
;                             const u32x4e g = *(const u32x4e*)(aux1 + off);
;                             v0[0] *= bflo(g.x); v0[1] *= bfhi(g.x); v0[2] *= bflo(g.y); v0[3] *= bfhi(g.y);
;                             v1[0] *= bflo(g.z); v1[1] *= bfhi(g.z); v1[2] *= bflo(g.w); v1[3] *= bfhi(g.w);
;                         } else {
;                             const u32x4e y = *(const u32x4e*)(aux1 + off); const u32x4e g = *(const u32x4e*)(aux2 + off);
;                             v0[0] = bflo(y.x) + bflo(g.x) * v0[0]; v0[1] = bfhi(y.x) + bfhi(g.x) * v0[1]; v0[2] = bflo(y.y) + bflo(g.y) * v0[2]; v0[3] = bfhi(y.y) + bfhi(g.y) * v0[3];
;                             v1[0] = bflo(y.z) + bflo(g.z) * v1[0]; v1[1] = bfhi(y.z) + bfhi(g.z) * v1[1]; v1[2] = bflo(y.w) + bflo(g.w) * v1[2]; v1[3] = bfhi(y.w) + bfhi(g.w) * v1[3];
;                         }
;                         u32x4e w; w.x = cvt_pk_bf16(v0[0], v0[1]); w.y = cvt_pk_bf16(v0[2], v0[3]); w.z = cvt_pk_bf16(v1[0], v1[1]); w.w = cvt_pk_bf16(v1[2], v1[3]);
;                         *(u32x4e*)(base + off) = w;
	v_cvt_pk_bf16_f32 v178, v32, v33
	v_cvt_pk_bf16_f32 v179, v34, v35
	global_store_dwordx4 v[150:151], v[176:179], off offset:256
	v_lshl_add_u64 v[150:151], v[150:151], 0, s[16:17]
	v_mul_f32_e32 v28, v28, v188
	v_mul_f32_e32 v29, v29, v188
	v_mul_f32_e32 v30, v30, v188
	v_mul_f32_e32 v31, v31, v188
	v_mul_f32_e32 v24, v24, v188
	v_mul_f32_e32 v25, v25, v188
	v_mul_f32_e32 v26, v26, v188
	v_mul_f32_e32 v27, v27, v188
	v_mul_f32_e32 v28, 0xbfb8aa3b, v28
	v_mul_f32_e32 v29, 0xbfb8aa3b, v29
	v_mul_f32_e32 v30, 0xbfb8aa3b, v30
	v_mul_f32_e32 v31, 0xbfb8aa3b, v31
	v_mul_f32_e32 v24, 0xbfb8aa3b, v24
	v_mul_f32_e32 v25, 0xbfb8aa3b, v25
	v_mul_f32_e32 v26, 0xbfb8aa3b, v26
	v_mul_f32_e32 v27, 0xbfb8aa3b, v27
	v_exp_f32_e32 v28, v28
	v_exp_f32_e32 v29, v29
	v_exp_f32_e32 v30, v30
	v_exp_f32_e32 v31, v31
	v_exp_f32_e32 v24, v24
	v_exp_f32_e32 v25, v25
	v_exp_f32_e32 v26, v26
	v_exp_f32_e32 v27, v27
	v_add_f32_e32 v28, 1.0, v28
	v_add_f32_e32 v29, 1.0, v29
	v_add_f32_e32 v30, 1.0, v30
	v_add_f32_e32 v31, 1.0, v31
	v_add_f32_e32 v24, 1.0, v24
	v_add_f32_e32 v25, 1.0, v25
	v_add_f32_e32 v26, 1.0, v26
	v_add_f32_e32 v27, 1.0, v27
	v_rcp_f32_e32 v28, v28
	v_rcp_f32_e32 v29, v29
	v_rcp_f32_e32 v30, v30
	v_rcp_f32_e32 v31, v31
	v_rcp_f32_e32 v24, v24
	v_rcp_f32_e32 v25, v25
	v_rcp_f32_e32 v26, v26
	v_rcp_f32_e32 v27, v27
	s_nop 0
	v_cvt_pk_bf16_f32 v172, v28, v29
	v_cvt_pk_bf16_f32 v173, v30, v31
	v_cvt_pk_bf16_f32 v174, v24, v25
	v_cvt_pk_bf16_f32 v175, v26, v27
	global_store_dwordx4 v[150:151], v[172:175], off
	v_mul_f32_e32 v20, v20, v188
	v_mul_f32_e32 v21, v21, v188
	v_mul_f32_e32 v22, v22, v188
	v_mul_f32_e32 v23, v23, v188
	v_mul_f32_e32 v16, v16, v188
	v_mul_f32_e32 v17, v17, v188
	v_mul_f32_e32 v18, v18, v188
	v_mul_f32_e32 v19, v19, v188
	v_mul_f32_e32 v20, 0xbfb8aa3b, v20
	v_mul_f32_e32 v21, 0xbfb8aa3b, v21
	v_mul_f32_e32 v22, 0xbfb8aa3b, v22
	v_mul_f32_e32 v23, 0xbfb8aa3b, v23
	v_mul_f32_e32 v16, 0xbfb8aa3b, v16
	v_mul_f32_e32 v17, 0xbfb8aa3b, v17
	v_mul_f32_e32 v18, 0xbfb8aa3b, v18
	v_mul_f32_e32 v19, 0xbfb8aa3b, v19
	v_exp_f32_e32 v20, v20
	v_exp_f32_e32 v21, v21
	v_exp_f32_e32 v22, v22
	v_exp_f32_e32 v23, v23
	v_exp_f32_e32 v16, v16
	v_exp_f32_e32 v17, v17
	v_exp_f32_e32 v18, v18
	v_exp_f32_e32 v19, v19
	v_add_f32_e32 v20, 1.0, v20
	v_add_f32_e32 v21, 1.0, v21
	v_add_f32_e32 v22, 1.0, v22
	v_add_f32_e32 v23, 1.0, v23
	v_add_f32_e32 v16, 1.0, v16
	v_add_f32_e32 v17, 1.0, v17
	v_add_f32_e32 v18, 1.0, v18
	v_add_f32_e32 v19, 1.0, v19
	v_rcp_f32_e32 v20, v20
	v_rcp_f32_e32 v21, v21
	v_rcp_f32_e32 v22, v22
	v_rcp_f32_e32 v23, v23
	v_rcp_f32_e32 v16, v16
	v_rcp_f32_e32 v17, v17
	v_rcp_f32_e32 v18, v18
	v_rcp_f32_e32 v19, v19
	s_nop 0
	v_cvt_pk_bf16_f32 v176, v20, v21
	v_cvt_pk_bf16_f32 v177, v22, v23
	v_cvt_pk_bf16_f32 v178, v16, v17
	v_cvt_pk_bf16_f32 v179, v18, v19
	global_store_dwordx4 v[150:151], v[176:179], off offset:256
	v_lshl_add_u64 v[150:151], v[150:151], 0, s[16:17]
	v_mul_f32_e32 v12, v12, v189
	v_mul_f32_e32 v13, v13, v189
	v_mul_f32_e32 v14, v14, v189
	v_mul_f32_e32 v15, v15, v189
	v_mul_f32_e32 v8, v8, v189
	v_mul_f32_e32 v9, v9, v189
	v_mul_f32_e32 v10, v10, v189
	v_mul_f32_e32 v11, v11, v189
	v_mul_f32_e32 v12, 0xbfb8aa3b, v12
	v_mul_f32_e32 v13, 0xbfb8aa3b, v13
	v_mul_f32_e32 v14, 0xbfb8aa3b, v14
	v_mul_f32_e32 v15, 0xbfb8aa3b, v15
	v_mul_f32_e32 v8, 0xbfb8aa3b, v8
	v_mul_f32_e32 v9, 0xbfb8aa3b, v9
	v_mul_f32_e32 v10, 0xbfb8aa3b, v10
	v_mul_f32_e32 v11, 0xbfb8aa3b, v11
	v_exp_f32_e32 v12, v12
	v_exp_f32_e32 v13, v13
	v_exp_f32_e32 v14, v14
	v_exp_f32_e32 v15, v15
	v_exp_f32_e32 v8, v8
	v_exp_f32_e32 v9, v9
	v_exp_f32_e32 v10, v10
	v_exp_f32_e32 v11, v11
	v_add_f32_e32 v12, 1.0, v12
	v_add_f32_e32 v13, 1.0, v13
	v_add_f32_e32 v14, 1.0, v14
	v_add_f32_e32 v15, 1.0, v15
	v_add_f32_e32 v8, 1.0, v8
	v_add_f32_e32 v9, 1.0, v9
	v_add_f32_e32 v10, 1.0, v10
	v_add_f32_e32 v11, 1.0, v11
	v_rcp_f32_e32 v12, v12
	v_rcp_f32_e32 v13, v13
	v_rcp_f32_e32 v14, v14
	v_rcp_f32_e32 v15, v15
	v_rcp_f32_e32 v8, v8
	v_rcp_f32_e32 v9, v9
	v_rcp_f32_e32 v10, v10
	v_rcp_f32_e32 v11, v11
	s_nop 0
	v_cvt_pk_bf16_f32 v172, v12, v13
	v_cvt_pk_bf16_f32 v173, v14, v15
	v_cvt_pk_bf16_f32 v174, v8, v9
	v_cvt_pk_bf16_f32 v175, v10, v11
	global_store_dwordx4 v[150:151], v[172:175], off
	v_mul_f32_e32 v4, v4, v189
	v_mul_f32_e32 v5, v5, v189
	v_mul_f32_e32 v6, v6, v189
	v_mul_f32_e32 v7, v7, v189
	v_mul_f32_e32 v0, v0, v189
	v_mul_f32_e32 v1, v1, v189
	v_mul_f32_e32 v2, v2, v189
	v_mul_f32_e32 v3, v3, v189
	v_mul_f32_e32 v4, 0xbfb8aa3b, v4
	v_mul_f32_e32 v5, 0xbfb8aa3b, v5
	v_mul_f32_e32 v6, 0xbfb8aa3b, v6
	v_mul_f32_e32 v7, 0xbfb8aa3b, v7
	v_mul_f32_e32 v0, 0xbfb8aa3b, v0
	v_mul_f32_e32 v1, 0xbfb8aa3b, v1
	v_mul_f32_e32 v2, 0xbfb8aa3b, v2
	v_mul_f32_e32 v3, 0xbfb8aa3b, v3
	v_exp_f32_e32 v4, v4
	v_exp_f32_e32 v5, v5
	v_exp_f32_e32 v6, v6
	v_exp_f32_e32 v7, v7
	v_exp_f32_e32 v0, v0
	v_exp_f32_e32 v1, v1
	v_exp_f32_e32 v2, v2
	v_exp_f32_e32 v3, v3
	v_add_f32_e32 v4, 1.0, v4
	v_add_f32_e32 v5, 1.0, v5
	v_add_f32_e32 v6, 1.0, v6
	v_add_f32_e32 v7, 1.0, v7
	v_add_f32_e32 v0, 1.0, v0
	v_add_f32_e32 v1, 1.0, v1
	v_add_f32_e32 v2, 1.0, v2
	v_add_f32_e32 v3, 1.0, v3
	v_rcp_f32_e32 v4, v4
	v_rcp_f32_e32 v5, v5
	v_rcp_f32_e32 v6, v6
	v_rcp_f32_e32 v7, v7
	v_rcp_f32_e32 v0, v0
	v_rcp_f32_e32 v1, v1
	v_rcp_f32_e32 v2, v2
	v_rcp_f32_e32 v3, v3
	s_nop 0
	v_cvt_pk_bf16_f32 v176, v4, v5
	v_cvt_pk_bf16_f32 v177, v6, v7
	v_cvt_pk_bf16_f32 v178, v0, v1
	v_cvt_pk_bf16_f32 v179, v2, v3
	global_store_dwordx4 v[150:151], v[176:179], off offset:256
	s_branch .LBB0_967
